# GEMM unit loop headers (in-proj, MLP-in): dropped the full vmcnt(0) drain; the previous epilogue's stores now retire at the first counted wait of the new unit
# speedup vs baseline: 1.0085x; 1.0085x over previous
; __device__ __forceinline__ int prow0(int pm) { return (pm >> 4) * LP + PADR + (pm & 15) * 256; }
; template <class Epi>
; __device__ __forceinline__ void gemm_phase(LAS unsigned char* lds, const bf16_t* Ag, const bf16_t* Btg, const int K, const int nM, const int nN, const Epi& E) {
;     ...
;         const int un = u + G; const bool has_next = un < nunits; const int pmn = has_next ? un % nM : pm, pnn = has_next ? un / nM : pn;
;         const char* nA = has_next ? (const char*)Ag + (size_t)prow0(pmn) * rstep : cA; const char* nB = has_next ? (const char*)Btg + (size_t)pnn * tstep : cB;
;     ...
; #pragma unroll
;         for (int a = 0; a < 2; ++a)
; #pragma unroll
;             for (int b = 0; b < 2; ++b)
; #pragma unroll
;                 for (int m = 0; m < 4; ++m)
; #pragma unroll
;                     for (int n = 0; n < 2; ++n) acc[a][b][m][n] = (f32x4){0.f, 0.f, 0.f, 0.f};
;         if (pmn != pm) par ^= 1;
;         u = un; pm = pmn; pn = pnn; cA = nA; cB = nB;
.LBB0_76:
	s_ashr_i32 s47, s12, 6
	s_and_b64 s[14:15], s[48:49], exec
	s_cselect_b32 s14, s68, s47
	s_ashr_i32 s15, s14, 31
	s_lshl_b64 s[14:15], s[14:15], 19
	s_add_u32 s44, s24, s14
	s_addc_u32 s45, s25, s15
	s_and_b64 s[14:15], s[48:49], exec
	s_cselect_b32 s15, s53, s45
	s_cselect_b32 s69, s52, s44
	s_cmp_eq_u32 s67, s66
	s_cselect_b64 s[54:55], -1, 0
	s_lshl_b32 s14, s64, 11
	s_xor_b32 s12, s14, 0x800
	s_add_i32 s70, s12, 0
	s_add_i32 s70, s70, 0x20000
	s_or_b64 s[48:49], s[48:49], s[54:55]
	s_add_u32 s71, s52, 0x100
	s_addc_u32 s72, s53, 0
	s_add_u32 s50, s50, 0x40080
	v_mov_b32_e32 v8, 0
	s_addc_u32 s51, s51, 0
	s_mov_b32 s73, -2
	v_mov_b32_e32 v9, v8
	v_mov_b32_e32 v10, v8
	v_mov_b32_e32 v11, v8
	v_mov_b32_e32 v12, v8
	v_mov_b32_e32 v13, v8
	v_mov_b32_e32 v14, v8
	v_mov_b32_e32 v15, v8
	v_mov_b32_e32 v24, v8
	v_mov_b32_e32 v25, v8
	v_mov_b32_e32 v26, v8
	v_mov_b32_e32 v27, v8
	v_mov_b32_e32 v28, v8
	v_mov_b32_e32 v29, v8
	v_mov_b32_e32 v30, v8
	v_mov_b32_e32 v31, v8
	v_mov_b32_e32 v40, v8
	v_mov_b32_e32 v41, v8
	v_mov_b32_e32 v42, v8
	v_mov_b32_e32 v43, v8
	v_mov_b32_e32 v44, v8
	v_mov_b32_e32 v45, v8
	v_mov_b32_e32 v46, v8
	v_mov_b32_e32 v47, v8
	v_mov_b32_e32 v56, v8
	v_mov_b32_e32 v57, v8
	v_mov_b32_e32 v58, v8
	v_mov_b32_e32 v59, v8
	v_mov_b32_e32 v60, v8
	v_mov_b32_e32 v61, v8
	v_mov_b32_e32 v62, v8
	v_mov_b32_e32 v63, v8
	v_mov_b32_e32 v72, v8
	v_mov_b32_e32 v73, v8
	v_mov_b32_e32 v74, v8
	v_mov_b32_e32 v75, v8
	v_mov_b32_e32 v76, v8
	v_mov_b32_e32 v77, v8
	v_mov_b32_e32 v78, v8
	v_mov_b32_e32 v79, v8
	v_mov_b32_e32 v88, v8
	v_mov_b32_e32 v89, v8
	v_mov_b32_e32 v90, v8
	v_mov_b32_e32 v91, v8
	v_mov_b32_e32 v92, v8
	v_mov_b32_e32 v93, v8
	v_mov_b32_e32 v94, v8
	v_mov_b32_e32 v95, v8
	v_mov_b32_e32 v104, v8
	v_mov_b32_e32 v105, v8
	v_mov_b32_e32 v106, v8
	v_mov_b32_e32 v107, v8
	v_mov_b32_e32 v108, v8
	v_mov_b32_e32 v109, v8
	v_mov_b32_e32 v110, v8
	v_mov_b32_e32 v111, v8
	v_mov_b32_e32 v120, v8
	v_mov_b32_e32 v121, v8
	v_mov_b32_e32 v122, v8
	v_mov_b32_e32 v123, v8
	v_mov_b32_e32 v144, v8
	v_mov_b32_e32 v145, v8
	v_mov_b32_e32 v146, v8
	v_mov_b32_e32 v147, v8
	v_mov_b32_e32 v80, v8
	v_mov_b32_e32 v81, v8
	v_mov_b32_e32 v82, v8
	v_mov_b32_e32 v83, v8
	v_mov_b32_e32 v84, v8
	v_mov_b32_e32 v85, v8
	v_mov_b32_e32 v86, v8
	v_mov_b32_e32 v87, v8
	v_mov_b32_e32 v96, v8
	v_mov_b32_e32 v97, v8
	v_mov_b32_e32 v98, v8
	v_mov_b32_e32 v99, v8
	v_mov_b32_e32 v100, v8
	v_mov_b32_e32 v101, v8
	v_mov_b32_e32 v102, v8
	v_mov_b32_e32 v103, v8
	v_mov_b32_e32 v112, v8
	v_mov_b32_e32 v113, v8
	v_mov_b32_e32 v114, v8
	v_mov_b32_e32 v115, v8
	v_mov_b32_e32 v116, v8
	v_mov_b32_e32 v117, v8
	v_mov_b32_e32 v118, v8
	v_mov_b32_e32 v119, v8
	v_mov_b32_e32 v160, v8
	v_mov_b32_e32 v161, v8
	v_mov_b32_e32 v162, v8
	v_mov_b32_e32 v163, v8
	v_mov_b32_e32 v164, v8
	v_mov_b32_e32 v165, v8
	v_mov_b32_e32 v166, v8
	v_mov_b32_e32 v167, v8
	v_mov_b32_e32 v68, v8
	v_mov_b32_e32 v69, v8
	v_mov_b32_e32 v70, v8
	v_mov_b32_e32 v71, v8
	v_mov_b32_e32 v64, v8
	v_mov_b32_e32 v65, v8
	v_mov_b32_e32 v66, v8
	v_mov_b32_e32 v67, v8
	v_mov_b32_e32 v52, v8
	v_mov_b32_e32 v53, v8
	v_mov_b32_e32 v54, v8
	v_mov_b32_e32 v55, v8
	v_mov_b32_e32 v48, v8
	v_mov_b32_e32 v49, v8
	v_mov_b32_e32 v50, v8
	v_mov_b32_e32 v51, v8
	v_mov_b32_e32 v36, v8
	v_mov_b32_e32 v37, v8
	v_mov_b32_e32 v38, v8
	v_mov_b32_e32 v39, v8
	v_mov_b32_e32 v32, v8
	v_mov_b32_e32 v33, v8
	v_mov_b32_e32 v34, v8
	v_mov_b32_e32 v35, v8
	v_mov_b32_e32 v20, v8
	v_mov_b32_e32 v21, v8
	v_mov_b32_e32 v22, v8
	v_mov_b32_e32 v23, v8
	v_mov_b32_e32 v16, v8
	v_mov_b32_e32 v17, v8
	v_mov_b32_e32 v18, v8
	v_mov_b32_e32 v19, v8
	s_branch .LBB0_79

; __device__ __forceinline__ int prow0(int pm) { return (pm >> 4) * LP + PADR + (pm & 15) * 256; }
; template <class Epi>
; __device__ __forceinline__ void gemm_phase(LAS unsigned char* lds, const bf16_t* Ag, const bf16_t* Btg, const int K, const int nM, const int nN, const Epi& E) {
;     ...
;         const int un = u + G; const bool has_next = un < nunits; const int pmn = has_next ? un % nM : pm, pnn = has_next ? un / nM : pn;
;         const char* nA = has_next ? (const char*)Ag + (size_t)prow0(pmn) * rstep : cA; const char* nB = has_next ? (const char*)Btg + (size_t)pnn * tstep : cB;
;     ...
; #pragma unroll
;         for (int a = 0; a < 2; ++a)
; #pragma unroll
;             for (int b = 0; b < 2; ++b)
; #pragma unroll
;                 for (int m = 0; m < 4; ++m)
; #pragma unroll
;                     for (int n = 0; n < 2; ++n) acc[a][b][m][n] = (f32x4){0.f, 0.f, 0.f, 0.f};
;         if (pmn != pm) par ^= 1;
;         u = un; pm = pmn; pn = pnn; cA = nA; cB = nB;
.LBB0_846:
	s_ashr_i32 s47, s26, 6
	s_and_b64 s[14:15], s[48:49], exec
	s_cselect_b32 s14, s69, s47
	s_ashr_i32 s15, s14, 31
	s_lshl_b64 s[14:15], s[14:15], 19
	s_add_u32 s44, s6, s14
	s_addc_u32 s45, s7, s15
	s_and_b64 s[14:15], s[48:49], exec
	s_cselect_b32 s14, s53, s45
	s_cselect_b32 s15, s52, s44
	s_cmp_eq_u32 s67, s68
	s_cselect_b64 s[54:55], -1, 0
	s_or_b64 s[54:55], s[42:43], s[54:55]
	v_lshlrev_b32_e32 v174, 11, v223
	s_or_b64 s[48:49], s[48:49], s[54:55]
	v_xor_b32_e32 v8, 0x800, v174
	s_add_u32 s70, s52, 0x100
	v_add_u32_e32 v8, 0, v8
	s_addc_u32 s71, s53, 0
	v_add_u32_e32 v128, 0x20000, v8
	s_add_u32 s50, s50, 0x40080
	v_mov_b32_e32 v8, 0
	s_addc_u32 s51, s51, 0
	s_mov_b32 s72, -2
	v_mov_b32_e32 v9, v8
	v_mov_b32_e32 v10, v8
	v_mov_b32_e32 v11, v8
	v_mov_b32_e32 v12, v8
	v_mov_b32_e32 v13, v8
	v_mov_b32_e32 v14, v8
	v_mov_b32_e32 v15, v8
	v_mov_b32_e32 v24, v8
	v_mov_b32_e32 v25, v8
	v_mov_b32_e32 v26, v8
	v_mov_b32_e32 v27, v8
	v_mov_b32_e32 v28, v8
	v_mov_b32_e32 v29, v8
	v_mov_b32_e32 v30, v8
	v_mov_b32_e32 v31, v8
	v_mov_b32_e32 v40, v8
	v_mov_b32_e32 v41, v8
	v_mov_b32_e32 v42, v8
	v_mov_b32_e32 v43, v8
	v_mov_b32_e32 v44, v8
	v_mov_b32_e32 v45, v8
	v_mov_b32_e32 v46, v8
	v_mov_b32_e32 v47, v8
	v_mov_b32_e32 v56, v8
	v_mov_b32_e32 v57, v8
	v_mov_b32_e32 v58, v8
	v_mov_b32_e32 v59, v8
	v_mov_b32_e32 v60, v8
	v_mov_b32_e32 v61, v8
	v_mov_b32_e32 v62, v8
	v_mov_b32_e32 v63, v8
	v_mov_b32_e32 v72, v8
	v_mov_b32_e32 v73, v8
	v_mov_b32_e32 v74, v8
	v_mov_b32_e32 v75, v8
	v_mov_b32_e32 v76, v8
	v_mov_b32_e32 v77, v8
	v_mov_b32_e32 v78, v8
	v_mov_b32_e32 v79, v8
	v_mov_b32_e32 v88, v8
	v_mov_b32_e32 v89, v8
	v_mov_b32_e32 v90, v8
	v_mov_b32_e32 v91, v8
	v_mov_b32_e32 v92, v8
	v_mov_b32_e32 v93, v8
	v_mov_b32_e32 v94, v8
	v_mov_b32_e32 v95, v8
	v_mov_b32_e32 v104, v8
	v_mov_b32_e32 v105, v8
	v_mov_b32_e32 v106, v8
	v_mov_b32_e32 v107, v8
	v_mov_b32_e32 v108, v8
	v_mov_b32_e32 v109, v8
	v_mov_b32_e32 v110, v8
	v_mov_b32_e32 v111, v8
	v_mov_b32_e32 v120, v8
	v_mov_b32_e32 v121, v8
	v_mov_b32_e32 v122, v8
	v_mov_b32_e32 v123, v8
	v_mov_b32_e32 v124, v8
	v_mov_b32_e32 v125, v8
	v_mov_b32_e32 v126, v8
	v_mov_b32_e32 v127, v8
	v_mov_b32_e32 v80, v8
	v_mov_b32_e32 v81, v8
	v_mov_b32_e32 v82, v8
	v_mov_b32_e32 v83, v8
	v_mov_b32_e32 v84, v8
	v_mov_b32_e32 v85, v8
	v_mov_b32_e32 v86, v8
	v_mov_b32_e32 v87, v8
	v_mov_b32_e32 v96, v8
	v_mov_b32_e32 v97, v8
	v_mov_b32_e32 v98, v8
	v_mov_b32_e32 v99, v8
	v_mov_b32_e32 v100, v8
	v_mov_b32_e32 v101, v8
	v_mov_b32_e32 v102, v8
	v_mov_b32_e32 v103, v8
	v_mov_b32_e32 v112, v8
	v_mov_b32_e32 v113, v8
	v_mov_b32_e32 v114, v8
	v_mov_b32_e32 v115, v8
	v_mov_b32_e32 v116, v8
	v_mov_b32_e32 v117, v8
	v_mov_b32_e32 v118, v8
	v_mov_b32_e32 v119, v8
	v_mov_b32_e32 v140, v8
	v_mov_b32_e32 v141, v8
	v_mov_b32_e32 v142, v8
	v_mov_b32_e32 v143, v8
	v_mov_b32_e32 v152, v8
	v_mov_b32_e32 v153, v8
	v_mov_b32_e32 v154, v8
	v_mov_b32_e32 v155, v8
	v_mov_b32_e32 v68, v8
	v_mov_b32_e32 v69, v8
	v_mov_b32_e32 v70, v8
	v_mov_b32_e32 v71, v8
	v_mov_b32_e32 v64, v8
	v_mov_b32_e32 v65, v8
	v_mov_b32_e32 v66, v8
	v_mov_b32_e32 v67, v8
	v_mov_b32_e32 v52, v8
	v_mov_b32_e32 v53, v8
	v_mov_b32_e32 v54, v8
	v_mov_b32_e32 v55, v8
	v_mov_b32_e32 v48, v8
	v_mov_b32_e32 v49, v8
	v_mov_b32_e32 v50, v8
	v_mov_b32_e32 v51, v8
	v_mov_b32_e32 v36, v8
	v_mov_b32_e32 v37, v8
	v_mov_b32_e32 v38, v8
	v_mov_b32_e32 v39, v8
	v_mov_b32_e32 v32, v8
	v_mov_b32_e32 v33, v8
	v_mov_b32_e32 v34, v8
	v_mov_b32_e32 v35, v8
	v_mov_b32_e32 v20, v8
	v_mov_b32_e32 v21, v8
	v_mov_b32_e32 v22, v8
	v_mov_b32_e32 v23, v8
	v_mov_b32_e32 v16, v8
	v_mov_b32_e32 v17, v8
	v_mov_b32_e32 v18, v8
	v_mov_b32_e32 v19, v8
	s_branch .LBB0_849
